# LayerNorm loop: the two row loads software-pipelined one iteration ahead through shadow registers
# speedup vs baseline: 1.0069x; 1.0069x over previous
; DI int tidx() { int t = threadIdx.x; asm volatile("" : "+v"(t)); return t; }
; DI void phase_ln(const P& p, int l) {
;   const int tid = tidx(); const int lane = tid & 63, w = tid >> 6;
;   const int nrows = (l == 0) ? MALL : MLAT;
;   const float* Zb = (const float*)p.slab;
;   const float* lg = p.ln_g + l * 1024;
;   const float* lb = p.ln_b + l * 1024;
;   const int gw = blockIdx.x * 8 + w, nw = gridDim.x * 8;
;   const int per = (nrows + nw - 1) / nw;
;   const int r0 = gw * per, r1 = (r0 + per < nrows) ? r0 + per : nrows;
;   float4 g4[4], b4[4];
; #pragma unroll
;   for (int i = 0; i < 4; ++i) {
;     g4[i] = *(const float4*)(lg + i * 256 + lane * 4);
;     b4[i] = *(const float4*)(lb + i * 256 + lane * 4);
;   }
;   for (int row = r0; row < r1; row += 2) {
;     const bool two = row + 1 < r1;
;     const int rowb = two ? row + 1 : row;
;     float4 v[2][4];
; #pragma unroll
;     for (int i = 0; i < 4; ++i) {
;       v[0][i] = *(const float4*)(Zb + (size_t)row * 1024 + i * 256 + lane * 4);
;       v[1][i] = *(const float4*)(Zb + (size_t)rowb * 1024 + i * 256 + lane * 4);
;     }
.LBB0_27:
	v_writelane_b32 v255, s48, 50
	s_add_i32 s23, s48, -2
	s_ashr_i32 s50, s23, 2
	s_and_b32 s24, s23, 3
	v_writelane_b32 v255, s49, 51
	s_cmp_lt_i32 s24, 2
	s_mov_b64 s[0:1], -1
	s_cbranch_scc1 .LBB0_74
	s_cmp_gt_i32 s24, 2
	s_cbranch_scc0 .LBB0_66
	v_mov_b32_e32 v34, v195
	s_load_dword s2, s[76:77], 0x0
	s_cmp_lt_u32 s23, 4
	s_cselect_b64 s[0:1], -1, 0
	s_and_b64 s[26:27], s[0:1], exec
	s_cselect_b32 s25, 0x9000, s21
	s_waitcnt lgkmcnt(0)
	s_lshl_b32 s2, s2, 3
	s_abs_i32 s26, s2
	v_cvt_f32_u32_e32 v0, s26
	v_ashrrev_i32_e32 v2, 6, v34
	v_readlane_b32 s27, v254, 3
	v_rcp_iflag_f32_e32 v0, v0
	s_nop 0
	v_add_u32_e32 v2, s27, v2
	s_add_i32 s27, s25, s2
	s_add_i32 s40, s27, -1
	v_mul_f32_e32 v0, 0x4f7ffffe, v0
	v_cvt_u32_f32_e32 v0, v0
	s_sub_i32 s27, 1, s27
	s_xor_b32 s2, s40, s2
	s_max_i32 s27, s40, s27
	s_sub_i32 s40, 0, s26
	v_readfirstlane_b32 s41, v0
	s_mul_i32 s40, s40, s41
	s_mul_hi_u32 s40, s41, s40
	s_add_i32 s41, s41, s40
	s_mul_hi_u32 s40, s27, s41
	s_mul_i32 s41, s40, s26
	s_sub_i32 s27, s27, s41
	s_ashr_i32 s2, s2, 31
	s_add_i32 s41, s40, 1
	s_sub_i32 s42, s27, s26
	s_cmp_ge_u32 s27, s26
	s_cselect_b32 s40, s41, s40
	s_cselect_b32 s27, s42, s27
	s_add_i32 s41, s40, 1
	s_cmp_ge_u32 s27, s26
	s_cselect_b32 s26, s41, s40
	s_xor_b32 s26, s26, s2
	s_sub_i32 s2, s26, s2
	v_mul_lo_u32 v62, s2, v2
	v_add_u32_e32 v0, s2, v62
	v_min_i32_e32 v65, s25, v0
	v_cmp_lt_i32_e32 vcc, v62, v65
	s_and_saveexec_b64 s[44:45], vcc
	s_cbranch_execz .LBB0_65
	s_lshl_b32 s26, s50, 10
	s_ashr_i32 s27, s26, 31
	s_lshl_b64 s[26:27], s[26:27], 2
	v_readlane_b32 s52, v255, 36
	v_readlane_b32 s53, v255, 37
	s_add_u32 s40, s52, s26
	v_lshlrev_b32_e32 v0, 2, v34
	v_readlane_b32 s54, v255, 38
	s_addc_u32 s41, s53, s27
	v_and_b32_e32 v64, 0xfc, v0
	v_readlane_b32 s55, v255, 39
	s_add_u32 s26, s54, s26
	v_lshlrev_b32_e32 v0, 2, v64
	s_addc_u32 s27, s55, s27
	global_load_dwordx4 v[2:5], v0, s[40:41]
	global_load_dwordx4 v[6:9], v0, s[40:41] offset:1024
	global_load_dwordx4 v[10:13], v0, s[26:27]
	global_load_dwordx4 v[14:17], v0, s[26:27] offset:1024
	global_load_dwordx4 v[18:21], v0, s[40:41] offset:2048
	global_load_dwordx4 v[22:25], v0, s[40:41] offset:3072
	global_load_dwordx4 v[26:29], v0, s[26:27] offset:2048
	global_load_dwordx4 v[30:33], v0, s[26:27] offset:3072
	v_and_b32_e32 v35, 64, v226
	v_add_u32_e32 v35, 64, v35
	v_xor_b32_e32 v36, 32, v226
	v_cmp_lt_i32_e32 vcc, v36, v35
	v_lshl_add_u64 v[66:67], s[18:19], 0, v[0:1]
	v_lshl_add_u64 v[74:75], s[10:11], 0, v[0:1]
	v_cndmask_b32_e32 v36, v226, v36, vcc
	v_lshlrev_b32_e32 v69, 2, v36
	v_xor_b32_e32 v36, 16, v226
	v_cmp_lt_i32_e32 vcc, v36, v35
	v_lshlrev_b32_e32 v0, 1, v64
	v_ashrrev_i32_e32 v63, 31, v62
	v_cndmask_b32_e32 v36, v226, v36, vcc
	v_lshlrev_b32_e32 v71, 2, v36
	v_xor_b32_e32 v36, 8, v226
	v_cmp_lt_i32_e32 vcc, v36, v35
	v_lshl_add_u64 v[76:77], s[16:17], 0, v[0:1]
	v_and_b32_e32 v0, 63, v34
	v_cndmask_b32_e32 v36, v226, v36, vcc
	v_lshlrev_b32_e32 v73, 2, v36
	v_xor_b32_e32 v36, 4, v226
	v_cmp_lt_i32_e32 vcc, v36, v35
	v_readlane_b32 s26, v255, 21
	s_cmp_eq_u32 s50, 1
	v_cndmask_b32_e32 v36, v226, v36, vcc
	v_lshlrev_b32_e32 v102, 2, v36
	v_xor_b32_e32 v36, 2, v226
	v_cmp_lt_i32_e32 vcc, v36, v35
	v_readlane_b32 s27, v255, 22
	s_cselect_b64 s[46:47], -1, 0
	v_cndmask_b32_e32 v36, v226, v36, vcc
	v_lshlrev_b32_e32 v103, 2, v36
	v_xor_b32_e32 v36, 1, v226
	v_cmp_lt_i32_e32 vcc, v36, v35
	v_or_b32_e32 v68, 0x100, v64
	v_or_b32_e32 v70, 0x200, v64
	v_cndmask_b32_e32 v35, v226, v36, vcc
	v_lshlrev_b32_e32 v104, 2, v35
	v_lshlrev_b64 v[34:35], 12, v[62:63]
	v_lshl_add_u64 v[80:81], s[18:19], 0, v[34:35]
	v_lshl_add_u64 v[82:83], s[10:11], 0, v[34:35]
	v_lshlrev_b64 v[34:35], 11, v[62:63]
	v_lshl_or_b32 v34, v0, 3, v34
	v_or_b32_e32 v72, 0x300, v64
	v_lshlrev_b32_e32 v78, 4, v0
	v_mov_b32_e32 v79, v1
	v_lshl_add_u64 v[84:85], s[26:27], 0, v[34:35]
	s_mov_b64 s[48:49], 0
	v_readlane_b32 s56, v255, 40
	v_readlane_b32 s57, v255, 41
	v_readlane_b32 s58, v255, 42
	v_readlane_b32 s59, v255, 43
	v_mov_b32_e32 v244, v62
	v_mov_b32_e32 v232, 0
	v_mov_b32_e32 v233, 0
	v_lshl_add_u64 v[234:235], v[80:81], 0, v[232:233]
	v_lshl_add_u64 v[234:235], v[234:235], 0, v[78:79]
	v_add_u32_e32 v238, 1, v244
	v_cmp_lt_i32_e64 s[100:101], v238, v65
	s_nop 1
	v_cndmask_b32_e64 v238, v244, v238, s[100:101]
	v_ashrrev_i32_e32 v239, 31, v238
	v_lshlrev_b64 v[238:239], 12, v[238:239]
	v_lshl_add_u64 v[238:239], v[66:67], 0, v[238:239]
	global_load_dwordx4 v[196:199], v[234:235], off
	global_load_dwordx4 v[200:203], v[234:235], off offset:1024
	global_load_dwordx4 v[204:207], v[234:235], off offset:2048
	global_load_dwordx4 v[208:211], v[234:235], off offset:3072
	global_load_dwordx4 v[212:215], v[238:239], off
	global_load_dwordx4 v[216:219], v[238:239], off offset:1024
	global_load_dwordx4 v[220:223], v[238:239], off offset:2048
	global_load_dwordx4 v[228:231], v[238:239], off offset:3072
	s_branch .LBB0_32

; DI void phase_ln(const P& p, int l) {
;     ...
;   for (int row = r0; row < r1; row += 2) {
;     const bool two = row + 1 < r1;
;     const int rowb = two ? row + 1 : row;
;     float4 v[2][4];
; #pragma unroll
;     for (int i = 0; i < 4; ++i) {
;       v[0][i] = *(const float4*)(Zb + (size_t)row * 1024 + i * 256 + lane * 4);
;       v[1][i] = *(const float4*)(Zb + (size_t)rowb * 1024 + i * 256 + lane * 4);
;     }
;     ...
;       const int mr = rr < MLAT ? (rr >> 11) : 16;
;       const float* md = p.mod + (size_t)(1 * 17 + mr) * 3072;
; #pragma unroll
;       for (int i = 0; i < 4; ++i) {
;         const int col = i * 256 + lane * 4;
;         float4 y;
;         y.x = v[h][i].x * rstd * g4[i].x + b4[i].x;
;         y.y = v[h][i].y * rstd * g4[i].y + b4[i].y;
;         y.z = v[h][i].z * rstd * g4[i].z + b4[i].z;
;         y.w = v[h][i].w * rstd * g4[i].w + b4[i].w;
;         if (l == 1 || rr < MLAT) *(float4*)(p.out + (size_t)rr * 1024 + col) = y;
;         if (l == 0) {
;           const float4 sh = *(const float4*)(md + col), sc = *(const float4*)(md + 1024 + col);
.LBB0_32:
	s_waitcnt vmcnt(0)
	v_mov_b32_e32 v34, v212
	v_mov_b32_e32 v35, v213
	v_mov_b32_e32 v36, v214
	v_mov_b32_e32 v37, v215
	v_mov_b32_e32 v46, v216
	v_mov_b32_e32 v47, v217
	v_mov_b32_e32 v48, v218
	v_mov_b32_e32 v49, v219
	v_mov_b32_e32 v42, v220
	v_mov_b32_e32 v43, v221
	v_mov_b32_e32 v44, v222
	v_mov_b32_e32 v45, v223
	v_mov_b32_e32 v38, v228
	v_mov_b32_e32 v39, v229
	v_mov_b32_e32 v40, v230
	v_mov_b32_e32 v41, v231
	v_mov_b32_e32 v50, v208
	v_mov_b32_e32 v51, v209
	v_mov_b32_e32 v52, v210
	v_mov_b32_e32 v53, v211
	v_mov_b32_e32 v54, v204
	v_mov_b32_e32 v55, v205
	v_mov_b32_e32 v56, v206
	v_mov_b32_e32 v57, v207
	v_mov_b32_e32 v58, v200
	v_mov_b32_e32 v59, v201
	v_mov_b32_e32 v60, v202
	v_mov_b32_e32 v61, v203
	v_mov_b32_e32 v240, v196
	v_mov_b32_e32 v241, v197
	v_mov_b32_e32 v242, v198
	v_mov_b32_e32 v243, v199
	s_andn2_b64 vcc, exec, s[0:1]
	s_cbranch_vccnz .Lln_nopf
	v_readlane_b32 s98, v255, 30
	v_readlane_b32 s99, v255, 31
	v_lshlrev_b32_e32 v114, 2, v64
	v_mov_b32_e32 v115, v1
	v_min_i32_e32 v116, 0x8000, v62
	v_ashrrev_i32_e32 v116, 11, v116
	v_add_u32_e32 v116, 17, v116
	v_mul_hi_i32_i24_e32 v119, 0x3000, v116
	v_mul_i32_i24_e32 v118, 0x3000, v116
	v_lshl_add_u64 v[118:119], s[98:99], 0, v[118:119]
	v_lshl_add_u64 v[120:121], v[118:119], 0, s[90:91]
	v_lshl_add_u64 v[118:119], v[118:119], 0, v[114:115]
	v_lshl_add_u64 v[120:121], v[120:121], 0, v[114:115]
	global_load_dwordx4 v[128:131], v[120:121], off
	global_load_dwordx4 v[132:135], v[118:119], off
	global_load_dwordx4 v[136:139], v[120:121], off offset:1024
	global_load_dwordx4 v[140:143], v[118:119], off offset:1024
	global_load_dwordx4 v[144:147], v[120:121], off offset:2048
	global_load_dwordx4 v[148:151], v[118:119], off offset:2048
	global_load_dwordx4 v[152:155], v[120:121], off offset:3072
	global_load_dwordx4 v[156:159], v[118:119], off offset:3072
	v_add_u32_e32 v116, 1, v62
	v_min_i32_e32 v116, 0x8000, v116
	v_ashrrev_i32_e32 v116, 11, v116
	v_add_u32_e32 v116, 17, v116
	v_mul_hi_i32_i24_e32 v123, 0x3000, v116
	v_mul_i32_i24_e32 v122, 0x3000, v116
	v_lshl_add_u64 v[122:123], s[98:99], 0, v[122:123]
	v_lshl_add_u64 v[124:125], v[122:123], 0, s[90:91]
	v_lshl_add_u64 v[122:123], v[122:123], 0, v[114:115]
	v_lshl_add_u64 v[124:125], v[124:125], 0, v[114:115]
	global_load_dwordx4 v[160:163], v[124:125], off
	global_load_dwordx4 v[164:167], v[122:123], off
	global_load_dwordx4 v[168:171], v[124:125], off offset:1024
	global_load_dwordx4 v[172:175], v[122:123], off offset:1024
	global_load_dwordx4 v[176:179], v[124:125], off offset:2048
	global_load_dwordx4 v[180:183], v[122:123], off offset:2048
	global_load_dwordx4 v[184:187], v[124:125], off offset:3072
	global_load_dwordx4 v[188:191], v[122:123], off offset:3072
; DI void phase_ln(const P& p, int l) {
;     ...
; #pragma unroll
;     for (int h = 0; h < 2; ++h) {
;       if (h && !two) break;
;       const int rr = h ? rowb : row;
;       float s = 0.f;
; #pragma unroll
;       for (int i = 0; i < 4; ++i) s += (v[h][i].x + v[h][i].y) + (v[h][i].z + v[h][i].w);
; #pragma unroll
;       for (int o = 32; o >= 1; o >>= 1) s += __shfl_xor(s, o);
;       const float mean = s * (1.f / 1024.f);
;       float q = 0.f;
; #pragma unroll
;       for (int i = 0; i < 4; ++i) {
;         v[h][i].x -= mean; v[h][i].y -= mean; v[h][i].z -= mean; v[h][i].w -= mean;
;         q += (v[h][i].x * v[h][i].x + v[h][i].y * v[h][i].y) + (v[h][i].z * v[h][i].z + v[h][i].w * v[h][i].w);
;       }
; #pragma unroll
;       for (int o = 32; o >= 1; o >>= 1) q += __shfl_xor(q, o);
;       const float rstd = rsqrtf(q * (1.f / 1024.f) + 1e-5f);
;       const int mr = rr < MLAT ? (rr >> 11) : 16;
;       const float* md = p.mod + (size_t)(1 * 17 + mr) * 3072;
; #pragma unroll
;       for (int i = 0; i < 4; ++i) {
;         const int col = i * 256 + lane * 4;
;         float4 y;
;         y.x = v[h][i].x * rstd * g4[i].x + b4[i].x;
;         y.y = v[h][i].y * rstd * g4[i].y + b4[i].y;
;         y.z = v[h][i].z * rstd * g4[i].z + b4[i].z;
;         y.w = v[h][i].w * rstd * g4[i].w + b4[i].w;
;         if (l == 1 || rr < MLAT) *(float4*)(p.out + (size_t)rr * 1024 + col) = y;
.Lln_nopf:
	v_add_u32_e32 v63, 1, v62
	v_cmp_lt_i32_e64 s[40:41], v63, v65
	v_cmp_gt_i32_e32 vcc, s21, v62
	v_cndmask_b32_e64 v86, v62, v63, s[40:41]
	v_ashrrev_i32_e32 v87, 31, v86
	v_lshlrev_b64 v[88:89], 12, v[86:87]
	v_add_u32_e32 v244, 2, v62
	v_cmp_lt_i32_e64 s[26:27], v244, v65
	v_mov_b32_e32 v232, 0x2000
	s_nop 0
	v_cndmask_b32_e64 v244, v62, v244, s[26:27]
	v_cndmask_b32_e64 v232, 0, v232, s[26:27]
	v_mov_b32_e32 v233, 0
	v_lshl_add_u64 v[234:235], v[80:81], 0, v[232:233]
	v_lshl_add_u64 v[234:235], v[234:235], 0, v[78:79]
	v_add_u32_e32 v238, 1, v244
	v_cmp_lt_i32_e64 s[100:101], v238, v65
	s_nop 1
	v_cndmask_b32_e64 v238, v244, v238, s[100:101]
	v_ashrrev_i32_e32 v239, 31, v238
	v_lshlrev_b64 v[238:239], 12, v[238:239]
	v_lshl_add_u64 v[238:239], v[66:67], 0, v[238:239]
	global_load_dwordx4 v[196:199], v[234:235], off
	global_load_dwordx4 v[200:203], v[234:235], off offset:1024
	global_load_dwordx4 v[204:207], v[234:235], off offset:2048
	global_load_dwordx4 v[208:211], v[234:235], off offset:3072
	global_load_dwordx4 v[212:215], v[238:239], off
	global_load_dwordx4 v[216:219], v[238:239], off offset:1024
	global_load_dwordx4 v[220:223], v[238:239], off offset:2048
	global_load_dwordx4 v[228:231], v[238:239], off offset:3072
	s_or_b64 s[52:53], s[46:47], vcc
	v_mov_b32_e32 v0, v57
	s_waitcnt vmcnt(8)
	v_mov_b32_e32 v92, v58
	v_mov_b32_e32 v93, v60
	v_mov_b32_e32 v98, v59
	v_mov_b32_e32 v99, v61
	v_pk_add_f32 v[92:93], v[92:93], v[98:99]
	v_pk_add_f32 v[94:95], v[56:57], v[0:1]
	v_pk_add_f32 v[98:99], v[92:93], v[92:93] op_sel:[0,1] op_sel_hi:[1,0]
	v_mov_b32_e32 v90, v240
	v_mov_b32_e32 v91, v241
	v_mov_b32_e32 v92, v242
	v_mov_b32_e32 v93, v243
	v_mov_b32_e32 v0, v55
	v_pk_add_f32 v[96:97], v[54:55], v[0:1]
	v_mov_b32_e32 v95, v53
	v_mov_b32_e32 v97, v52
	v_mov_b32_e32 v99, v51
	v_pk_add_f32 v[94:95], v[96:97], v[94:95]
	s_waitcnt vmcnt(8)
	v_mov_b32_e32 v100, v90
	v_mov_b32_e32 v101, v92
	v_mov_b32_e32 v106, v91
	v_mov_b32_e32 v107, v93
	v_pk_add_f32 v[100:101], v[100:101], v[106:107]
	s_nop 0
	v_add_f32_e32 v0, v100, v101
	v_add_f32_e32 v100, 0, v0
	v_mov_b32_e32 v101, v50
	v_pk_add_f32 v[96:97], v[100:101], v[98:99]
	s_nop 0
	v_pk_add_f32 v[94:95], v[96:97], v[94:95]
	s_nop 0
	v_add_f32_e32 v0, v94, v95
	v_mov_b32_e32 v94, v0
	s_nop 1
	v_permlane32_swap_b32_e32 v0, v94
	v_add_f32_e32 v0, v0, v94
	v_mov_b32_e32 v94, v0
	s_nop 1
	v_permlane16_swap_b32_e32 v0, v94
	v_add_f32_e32 v0, v0, v94
	s_nop 1
	v_add_f32_dpp v0, v0, v0 row_ror:8 row_mask:0xf bank_mask:0xf
	s_nop 1
	v_mov_b32_dpp v94, v0 row_shl:4 row_mask:0xf bank_mask:0x5
	v_mov_b32_dpp v94, v0 row_shr:4 row_mask:0xf bank_mask:0xa
	v_add_f32_e32 v0, v0, v94
	s_nop 1
	v_add_f32_dpp v0, v0, v0 quad_perm:[2,3,0,1] row_mask:0xf bank_mask:0xf
	s_nop 1
	v_add_f32_dpp v0, v0, v0 quad_perm:[1,0,3,2] row_mask:0xf bank_mask:0xf
	v_mul_f32_e32 v0, 0x3a800000, v0
	v_pk_add_f32 v[96:97], v[90:91], v[0:1] op_sel_hi:[1,0] neg_lo:[0,1] neg_hi:[0,1]
	v_pk_add_f32 v[98:99], v[92:93], v[0:1] op_sel_hi:[1,0] neg_lo:[0,1] neg_hi:[0,1]
	v_mov_b32_e32 v92, v97
	v_mov_b32_e32 v93, v99
	v_mov_b32_e32 v90, v96
	v_mov_b32_e32 v91, v98
	v_pk_mul_f32 v[92:93], v[92:93], v[92:93]
	s_nop 0
	v_pk_fma_f32 v[90:91], v[90:91], v[90:91], v[92:93]
	v_pk_add_f32 v[92:93], v[58:59], v[0:1] op_sel_hi:[1,0] neg_lo:[0,1] neg_hi:[0,1]
	v_pk_add_f32 v[94:95], v[90:91], v[90:91] op_sel_hi:[0,1]
	v_pk_add_f32 v[90:91], v[60:61], v[0:1] op_sel_hi:[1,0] neg_lo:[0,1] neg_hi:[0,1]
	v_mov_b32_e32 v60, v93
	v_mov_b32_e32 v61, v91
	v_mov_b32_e32 v58, v92
	v_mov_b32_e32 v59, v90
	v_pk_mul_f32 v[60:61], v[60:61], v[60:61]
	s_nop 0
	v_pk_fma_f32 v[58:59], v[58:59], v[58:59], v[60:61]
	v_pk_add_f32 v[60:61], v[54:55], v[0:1] op_sel_hi:[1,0] neg_lo:[0,1] neg_hi:[0,1]
	v_pk_add_f32 v[100:101], v[58:59], v[58:59] op_sel_hi:[0,1]
	v_pk_add_f32 v[58:59], v[56:57], v[0:1] op_sel_hi:[1,0] neg_lo:[0,1] neg_hi:[0,1]
	v_mul_f32_e32 v54, v60, v60
	v_pk_fma_f32 v[106:107], v[60:61], v[60:61], v[54:55] op_sel_hi:[1,1,0]
	v_mul_f32_e32 v54, v58, v58
	v_pk_fma_f32 v[108:109], v[58:59], v[58:59], v[54:55] op_sel_hi:[1,1,0]
	v_pk_add_f32 v[56:57], v[50:51], v[0:1] op_sel_hi:[1,0] neg_lo:[0,1] neg_hi:[0,1]
	v_pk_add_f32 v[54:55], v[52:53], v[0:1] op_sel_hi:[1,0] neg_lo:[0,1] neg_hi:[0,1]
	v_pk_mul_f32 v[50:51], v[56:57], v[56:57]
	v_pk_mul_f32 v[52:53], v[54:55], v[54:55]
	v_mov_b32_e32 v106, v50
	v_mov_b32_e32 v108, v51
	v_mov_b32_e32 v94, v52
	v_mov_b32_e32 v100, v53
	v_pk_add_f32 v[50:51], v[106:107], v[108:109]
	v_pk_add_f32 v[52:53], v[94:95], v[100:101]
	s_nop 0
	v_pk_add_f32 v[50:51], v[50:51], v[52:53]
	s_nop 0
	v_add_f32_e32 v0, v50, v51
	v_mov_b32_e32 v50, v0
	s_nop 1
	v_permlane32_swap_b32_e32 v0, v50
	v_add_f32_e32 v0, v0, v50
	v_mov_b32_e32 v50, v0
	s_nop 1
	v_permlane16_swap_b32_e32 v0, v50
	v_add_f32_e32 v0, v0, v50
	s_nop 1
	v_add_f32_dpp v0, v0, v0 row_ror:8 row_mask:0xf bank_mask:0xf
	s_nop 1
	v_mov_b32_dpp v50, v0 row_shl:4 row_mask:0xf bank_mask:0x5
	v_mov_b32_dpp v50, v0 row_shr:4 row_mask:0xf bank_mask:0xa
	v_add_f32_e32 v0, v0, v50
	s_nop 1
	v_add_f32_dpp v0, v0, v0 quad_perm:[2,3,0,1] row_mask:0xf bank_mask:0xf
	s_nop 1
	v_add_f32_dpp v0, v0, v0 quad_perm:[1,0,3,2] row_mask:0xf bank_mask:0xf
	v_mov_b32_e32 v50, 0x3727c5ac
	v_fmamk_f32 v0, v0, 0x3a800000, v50
	v_cmp_gt_f32_e32 vcc, s37, v0
	v_mul_f32_e32 v50, 0x4b800000, v0
	s_nop 0
	v_cndmask_b32_e32 v0, v0, v50, vcc
	v_rsq_f32_e32 v0, v0
	s_nop 0
	v_mul_f32_e32 v50, 0x45800000, v0
	v_cndmask_b32_e32 v94, v0, v50, vcc
	v_pk_mul_f32 v[50:51], v[96:97], v[94:95] op_sel_hi:[1,0]
	v_pk_mul_f32 v[52:53], v[98:99], v[94:95] op_sel_hi:[1,0]
	v_pk_fma_f32 v[50:51], v[2:3], v[50:51], v[10:11]
	v_pk_fma_f32 v[52:53], v[4:5], v[52:53], v[12:13]
	v_lshl_add_u64 v[96:97], v[82:83], 0, v[78:79]
	s_and_saveexec_b64 s[42:43], s[52:53]
	s_cbranch_execz .LBB0_34
	global_store_dwordx4 v[96:97], v[50:53], off
